# PLE gate epilogue: per batch, the four row groups ssq partial loads and 12 of 16 residual/pp loads issued together (was one serial load->wait per group), rstd reductions interleaved, progressive vmcnt
# baseline (speedup 1.0000x reference)
.LBB0_948:
	s_lshl_b32 s10, s20, 8
	s_add_i32 s10, s10, s61
	v_mbcnt_lo_u32_b32 v124, -1, 0
	v_mbcnt_hi_u32_b32 v124, -1, v124
	s_nop 0
	v_ashrrev_i32_e32 v122, 1, v124
	v_and_or_b32 v208, v124, 15, s10
	s_lshl_b32 s10, s82, 8
	v_and_b32_e32 v122, -8, v122
	s_or_b32 s10, s10, s68
	v_add_u32_e32 v204, s10, v122
	v_ashrrev_i32_e32 v122, 2, v124
	v_and_b32_e32 v122, -4, v122
	v_ashrrev_i32_e32 v123, 31, v122
	v_ashrrev_i32_e32 v209, 31, v208
	v_ashrrev_i32_e32 v205, 31, v204
	v_lshl_add_u64 v[206:207], v[122:123], 2, s[6:7]
	v_lshlrev_b64 v[122:123], 10, v[208:209]
	v_lshl_add_u64 v[122:123], v[122:123], 0, v[204:205]
	v_lshlrev_b32_e32 v125, 2, v124
	v_lshlrev_b64 v[122:123], 1, v[122:123]
	v_xor_b32_e32 v229, 64, v125
	v_xor_b32_e32 v228, 0x80, v125
	v_cmp_gt_u32_e32 vcc, 16, v124
	v_lshl_add_u64 v[124:125], s[88:89], 0, v[122:123]
	v_lshl_add_u64 v[122:123], s[62:63], 0, v[122:123]
	v_lshlrev_b64 v[226:227], 6, v[208:209]
	v_or_b32_e32 v224, 16, v208
	v_ashrrev_i32_e32 v225, 31, v224
	v_lshlrev_b64 v[222:223], 6, v[224:225]
	v_or_b32_e32 v218, 32, v208
	v_ashrrev_i32_e32 v219, 31, v218
	v_lshlrev_b64 v[220:221], 6, v[218:219]
	v_or_b32_e32 v214, 48, v208
	v_ashrrev_i32_e32 v215, 31, v214
	v_lshlrev_b64 v[216:217], 6, v[214:215]
	v_lshl_add_u64 v[210:211], v[206:207], 0, v[216:217]
	v_lshl_add_u64 v[246:247], v[206:207], 0, v[226:227]
	v_lshl_add_u64 v[248:249], v[206:207], 0, v[222:223]
	global_load_dwordx4 v[138:141], v[246:247], off
	global_load_dwordx4 v[134:137], v[248:249], off
	v_lshl_add_u64 v[246:247], v[206:207], 0, v[220:221]
	global_load_dwordx4 v[126:129], v[246:247], off
	global_load_dwordx4 v[242:245], v[210:211], off
	global_load_dwordx4 v[190:193], v[124:125], off
	global_load_dwordx4 v[186:189], v[122:123], off
	global_load_dwordx4 v[182:185], v[124:125], off offset:256
	global_load_dwordx4 v[178:181], v[122:123], off offset:256
	v_lshlrev_b64 v[122:123], 10, v[224:225]
	v_lshl_add_u64 v[122:123], v[122:123], 0, v[204:205]
	v_lshlrev_b64 v[122:123], 1, v[122:123]
	v_lshl_add_u64 v[124:125], s[88:89], 0, v[122:123]
	v_lshl_add_u64 v[122:123], s[62:63], 0, v[122:123]
	global_load_dwordx4 v[174:177], v[124:125], off
	global_load_dwordx4 v[170:173], v[122:123], off
	global_load_dwordx4 v[166:169], v[124:125], off offset:256
	global_load_dwordx4 v[162:165], v[122:123], off offset:256
	v_lshlrev_b64 v[122:123], 10, v[218:219]
	v_lshl_add_u64 v[122:123], v[122:123], 0, v[204:205]
	v_lshlrev_b64 v[122:123], 1, v[122:123]
	v_lshl_add_u64 v[124:125], s[88:89], 0, v[122:123]
	v_lshl_add_u64 v[122:123], s[62:63], 0, v[122:123]
	global_load_dwordx4 v[158:161], v[124:125], off
	global_load_dwordx4 v[154:157], v[122:123], off
	global_load_dwordx4 v[146:149], v[124:125], off offset:256
	global_load_dwordx4 v[142:145], v[122:123], off offset:256
	s_waitcnt vmcnt(12)
	v_add_f32_e32 v138, v138, v139
	v_add_f32_e32 v139, v140, v141
	v_add_f32_e32 v134, v134, v135
	v_add_f32_e32 v135, v136, v137
	v_add_f32_e32 v126, v126, v127
	v_add_f32_e32 v127, v128, v129
	v_add_f32_e32 v138, v138, v139
	v_add_f32_e32 v134, v134, v135
	v_add_f32_e32 v126, v126, v127
	ds_bpermute_b32 v139, v229, v138
	ds_bpermute_b32 v135, v229, v134
	ds_bpermute_b32 v127, v229, v126
	s_waitcnt lgkmcnt(2)
	v_add_f32_e32 v138, v138, v139
	ds_bpermute_b32 v139, v228, v138
	s_waitcnt lgkmcnt(2)
	v_add_f32_e32 v234, v134, v135
	ds_bpermute_b32 v235, v228, v234
	s_waitcnt lgkmcnt(2)
	v_add_f32_e32 v232, v126, v127
	ds_bpermute_b32 v233, v228, v232
	s_waitcnt lgkmcnt(2)
	v_add_f32_e32 v138, v138, v139
	v_fmamk_f32 v138, v138, 0x3a800000, v240
	v_rsq_f32_e32 v236, v138
	v_lshlrev_b64 v[122:123], 10, v[214:215]
	v_lshl_add_u64 v[122:123], v[122:123], 0, v[204:205]
	v_lshlrev_b64 v[122:123], 1, v[122:123]
	v_lshl_add_u64 v[124:125], s[88:89], 0, v[122:123]
	v_lshl_add_u64 v[122:123], s[62:63], 0, v[122:123]
	global_load_dwordx4 v[138:141], v[124:125], off
	global_load_dwordx4 v[134:137], v[122:123], off
	global_load_dwordx4 v[126:129], v[124:125], off offset:256
	s_nop 0
	global_load_dwordx4 v[122:125], v[122:123], off offset:256
	v_mul_f32_e32 v152, v152, v236
	v_mul_f32_e32 v153, v153, v236
	v_mul_f32_e32 v152, 0xbfb8aa3b, v152
	v_mul_f32_e32 v153, 0xbfb8aa3b, v153
	v_mul_f32_e32 v130, v130, v236
	v_mul_f32_e32 v131, v131, v236
	v_exp_f32_e32 v152, v152
	v_exp_f32_e32 v153, v153
	v_mul_f32_e32 v130, 0xbfb8aa3b, v130
	v_mul_f32_e32 v131, 0xbfb8aa3b, v131
	v_exp_f32_e32 v130, v130
	v_exp_f32_e32 v131, v131
	v_add_f32_e32 v152, 1.0, v152
	v_add_f32_e32 v153, 1.0, v153
	v_rcp_f32_e32 v152, v152
	v_rcp_f32_e32 v153, v153
	v_add_f32_e32 v130, 1.0, v130
	v_add_f32_e32 v131, 1.0, v131
	v_rcp_f32_e32 v130, v130
	v_rcp_f32_e32 v131, v131
	v_mul_f32_e32 v150, v150, v236
	v_mul_f32_e32 v151, v151, v236
	v_mul_f32_e32 v150, 0xbfb8aa3b, v150
	v_mul_f32_e32 v151, 0xbfb8aa3b, v151
	v_exp_f32_e32 v150, v150
	v_exp_f32_e32 v151, v151
	v_mul_f32_e32 v118, v118, v236
	v_mul_f32_e32 v119, v119, v236
	v_add_f32_e32 v150, 1.0, v150
	v_add_f32_e32 v151, 1.0, v151
	v_rcp_f32_e32 v150, v150
	v_rcp_f32_e32 v151, v151
	v_mul_f32_e32 v118, 0xbfb8aa3b, v118
	v_mul_f32_e32 v119, 0xbfb8aa3b, v119
	v_mul_f32_e32 v120, v120, v236
	v_mul_f32_e32 v121, v121, v236
	v_exp_f32_e32 v118, v118
	v_exp_f32_e32 v119, v119
	v_mul_f32_e32 v120, 0xbfb8aa3b, v120
	v_mul_f32_e32 v121, 0xbfb8aa3b, v121
	v_mul_f32_e32 v114, v114, v236
	v_mul_f32_e32 v115, v115, v236
	v_exp_f32_e32 v120, v120
	v_exp_f32_e32 v121, v121
	v_mul_f32_e32 v114, 0xbfb8aa3b, v114
	v_mul_f32_e32 v115, 0xbfb8aa3b, v115
	v_exp_f32_e32 v114, v114
	v_exp_f32_e32 v115, v115
	v_add_f32_e32 v118, 1.0, v118
	v_add_f32_e32 v119, 1.0, v119
	v_rcp_f32_e32 v118, v118
	v_rcp_f32_e32 v119, v119
	v_add_f32_e32 v120, 1.0, v120
	v_add_f32_e32 v121, 1.0, v121
	v_rcp_f32_e32 v120, v120
	v_rcp_f32_e32 v121, v121
	v_add_f32_e32 v114, 1.0, v114
	v_add_f32_e32 v115, 1.0, v115
	v_rcp_f32_e32 v114, v114
	v_rcp_f32_e32 v115, v115
	s_waitcnt vmcnt(15)
	v_lshlrev_b32_e32 v238, 16, v190
	v_and_b32_e32 v239, 0xffff0000, v190
	v_lshlrev_b32_e32 v190, 16, v191
	v_and_b32_e32 v191, 0xffff0000, v191
	v_add_f32_e32 v210, v242, v243
	s_waitcnt vmcnt(14)
	v_lshlrev_b32_e32 v242, 16, v186
	v_and_b32_e32 v243, 0xffff0000, v186
	v_lshlrev_b32_e32 v186, 16, v187
	v_and_b32_e32 v187, 0xffff0000, v187
	v_pk_fma_f32 v[152:153], v[152:153], v[186:187], v[190:191]
	v_lshlrev_b32_e32 v186, 16, v192
	v_and_b32_e32 v187, 0xffff0000, v192
	v_lshlrev_b32_e32 v190, 16, v188
	v_and_b32_e32 v191, 0xffff0000, v188
	v_pk_fma_f32 v[186:187], v[130:131], v[190:191], v[186:187]
	v_mul_f32_e32 v130, v132, v236
	v_mul_f32_e32 v131, v133, v236
	v_mul_f32_e32 v130, 0xbfb8aa3b, v130
	v_mul_f32_e32 v131, 0xbfb8aa3b, v131
	v_exp_f32_e32 v130, v130
	v_exp_f32_e32 v131, v131
	v_add_f32_e32 v211, v244, v245
	v_add_f32_e32 v210, v210, v211
	ds_bpermute_b32 v211, v229, v210
	v_add_f32_e32 v130, 1.0, v130
	v_add_f32_e32 v131, 1.0, v131
	v_rcp_f32_e32 v130, v130
	v_rcp_f32_e32 v131, v131
	s_waitcnt lgkmcnt(0)
	v_add_f32_e32 v230, v210, v211
	v_lshlrev_b64 v[210:211], 11, v[208:209]
	v_pk_fma_f32 v[150:151], v[150:151], v[242:243], v[238:239]
	v_lshlrev_b32_e32 v132, 16, v193
	v_and_b32_e32 v133, 0xffff0000, v193
	v_lshlrev_b32_e32 v188, 16, v189
	v_and_b32_e32 v189, 0xffff0000, v189
	v_pk_fma_f32 v[188:189], v[130:131], v[188:189], v[132:133]
	v_cvt_pk_bf16_f32 v130, v150, v151
	v_lshl_add_u64 v[150:151], s[92:93], 0, v[210:211]
	v_cvt_pk_bf16_f32 v131, v152, v153
	v_cvt_pk_bf16_f32 v132, v186, v187
	v_cvt_pk_bf16_f32 v133, v188, v189
	v_lshl_add_u64 v[150:151], v[204:205], 1, v[150:151]
	global_store_dwordx4 v[150:151], v[130:133], off
	v_lshlrev_b32_e32 v152, 16, v130
	v_lshlrev_b32_e32 v153, 16, v131
	v_and_b32_e32 v130, 0xffff0000, v130
	v_and_b32_e32 v131, 0xffff0000, v131
	v_mul_f32_e32 v130, v130, v130
	v_mul_f32_e32 v131, v131, v131
	v_lshlrev_b32_e32 v186, 16, v132
	v_and_b32_e32 v132, 0xffff0000, v132
	v_fmac_f32_e32 v130, v152, v152
	v_fmac_f32_e32 v131, v153, v153
	v_add_f32_e32 v130, v130, v131
	v_mul_f32_e32 v131, v132, v132
	v_lshlrev_b32_e32 v187, 16, v133
	v_and_b32_e32 v133, 0xffff0000, v133
	v_fmac_f32_e32 v131, v186, v186
	v_add_f32_e32 v130, v131, v130
	v_mul_f32_e32 v131, v133, v133
	v_fmac_f32_e32 v131, v187, v187
	v_add_f32_e32 v152, v131, v130
	s_waitcnt vmcnt(14)
	v_lshlrev_b32_e32 v130, 16, v182
	v_and_b32_e32 v131, 0xffff0000, v182
	s_waitcnt vmcnt(13)
	v_lshlrev_b32_e32 v132, 16, v178
	v_and_b32_e32 v133, 0xffff0000, v178
	v_pk_fma_f32 v[118:119], v[118:119], v[132:133], v[130:131]
	v_lshlrev_b32_e32 v130, 16, v183
	v_and_b32_e32 v131, 0xffff0000, v183
	v_lshlrev_b32_e32 v132, 16, v179
	v_and_b32_e32 v133, 0xffff0000, v179
	v_pk_fma_f32 v[120:121], v[120:121], v[132:133], v[130:131]
	v_lshlrev_b32_e32 v130, 16, v184
	v_and_b32_e32 v131, 0xffff0000, v184
	v_lshlrev_b32_e32 v132, 16, v180
	v_and_b32_e32 v133, 0xffff0000, v180
	v_pk_fma_f32 v[130:131], v[114:115], v[132:133], v[130:131]
	v_mul_f32_e32 v114, v116, v236
	v_mul_f32_e32 v115, v117, v236
	v_mul_f32_e32 v114, 0xbfb8aa3b, v114
	v_mul_f32_e32 v115, 0xbfb8aa3b, v115
	v_exp_f32_e32 v114, v114
	v_exp_f32_e32 v115, v115
	v_lshlrev_b32_e32 v116, 16, v185
	v_and_b32_e32 v117, 0xffff0000, v185
	v_add_f32_e32 v114, 1.0, v114
	v_add_f32_e32 v115, 1.0, v115
	v_rcp_f32_e32 v114, v114
	v_rcp_f32_e32 v115, v115
	v_lshlrev_b32_e32 v132, 16, v181
	v_and_b32_e32 v133, 0xffff0000, v181
	ds_bpermute_b32 v231, v228, v230
	v_pk_fma_f32 v[132:133], v[114:115], v[132:133], v[116:117]
	v_cvt_pk_bf16_f32 v114, v118, v119
	v_cvt_pk_bf16_f32 v115, v120, v121
	v_cvt_pk_bf16_f32 v116, v130, v131
	v_cvt_pk_bf16_f32 v117, v132, v133
	global_store_dwordx4 v[150:151], v[114:117], off offset:256
	v_lshlrev_b32_e32 v118, 16, v114
	v_lshlrev_b32_e32 v119, 16, v115
	v_and_b32_e32 v114, 0xffff0000, v114
	v_and_b32_e32 v115, 0xffff0000, v115
	v_mul_f32_e32 v114, v114, v114
	v_fmac_f32_e32 v114, v118, v118
	v_mul_f32_e32 v115, v115, v115
	v_lshlrev_b32_e32 v120, 16, v116
	v_and_b32_e32 v116, 0xffff0000, v116
	v_add_f32_e32 v114, v114, v152
	v_fmac_f32_e32 v115, v119, v119
	v_add_f32_e32 v114, v115, v114
	v_mul_f32_e32 v115, v116, v116
	v_lshlrev_b32_e32 v121, 16, v117
	v_and_b32_e32 v117, 0xffff0000, v117
	v_fmac_f32_e32 v115, v120, v120
	v_add_f32_e32 v114, v115, v114
	v_mul_f32_e32 v115, v117, v117
	v_fmac_f32_e32 v115, v121, v121
	v_add_f32_e32 v114, v115, v114
	ds_bpermute_b32 v115, v229, v114
	s_waitcnt lgkmcnt(0)
	v_add_f32_e32 v114, v114, v115
	ds_bpermute_b32 v115, v228, v114
	s_and_saveexec_b64 s[10:11], vcc
	s_cbranch_execz .LBB0_950
	s_lshl_b32 s20, s82, 2
	v_lshl_add_u64 v[116:117], s[4:5], 0, v[226:227]
	s_ashr_i32 s21, s20, 31
	v_lshl_add_u64 v[116:117], s[20:21], 2, v[116:117]
	s_lshl_b32 s76, s19, 2
	v_lshl_add_u64 v[116:117], v[116:117], 0, s[76:77]
	s_waitcnt lgkmcnt(0)
	v_add_f32_e32 v114, v114, v115
	global_store_dword v[116:117], v114, off
.LBB0_950:
	s_or_b64 exec, exec, s[10:11]
	v_add_f32_e32 v114, v234, v235
	v_fmamk_f32 v114, v114, 0x3a800000, v240
	v_rsq_f32_e32 v118, v114
	s_waitcnt vmcnt(13)
	v_lshlrev_b32_e32 v116, 16, v170
	v_and_b32_e32 v117, 0xffff0000, v170
	v_mul_f32_e32 v110, v110, v118
	v_mul_f32_e32 v111, v111, v118
	v_mul_f32_e32 v110, 0xbfb8aa3b, v110
	v_mul_f32_e32 v111, 0xbfb8aa3b, v111
	v_mul_f32_e32 v112, v112, v118
	v_mul_f32_e32 v113, v113, v118
	v_exp_f32_e32 v114, v110
	v_exp_f32_e32 v111, v111
	v_mul_f32_e32 v112, 0xbfb8aa3b, v112
	v_mul_f32_e32 v113, 0xbfb8aa3b, v113
	v_mul_f32_e32 v106, v106, v118
	v_mul_f32_e32 v107, v107, v118
	v_exp_f32_e32 v112, v112
	v_exp_f32_e32 v113, v113
	v_mul_f32_e32 v106, 0xbfb8aa3b, v106
	v_mul_f32_e32 v107, 0xbfb8aa3b, v107
	v_exp_f32_e32 v106, v106
	v_exp_f32_e32 v107, v107
	v_mul_f32_e32 v108, v108, v118
	v_add_f32_e32 v114, 1.0, v114
	v_add_f32_e32 v111, 1.0, v111
	v_mul_f32_e32 v108, 0xbfb8aa3b, v108
	v_rcp_f32_e32 v114, v114
	s_waitcnt lgkmcnt(0)
	v_rcp_f32_e32 v115, v111
	v_add_f32_e32 v112, 1.0, v112
	v_add_f32_e32 v113, 1.0, v113
	v_exp_f32_e32 v119, v108
	v_mul_f32_e32 v108, v109, v118
	v_rcp_f32_e32 v112, v112
	v_rcp_f32_e32 v113, v113
	v_add_f32_e32 v106, 1.0, v106
	v_add_f32_e32 v107, 1.0, v107
	v_mul_f32_e32 v108, 0xbfb8aa3b, v108
	v_rcp_f32_e32 v106, v106
	v_rcp_f32_e32 v107, v107
	v_exp_f32_e32 v120, v108
	v_lshlrev_b32_e32 v110, 16, v174
	v_and_b32_e32 v111, 0xffff0000, v174
	v_pk_fma_f32 v[110:111], v[114:115], v[116:117], v[110:111]
	v_lshlrev_b32_e32 v114, 16, v175
	v_and_b32_e32 v115, 0xffff0000, v175
	v_lshlrev_b32_e32 v116, 16, v171
	v_and_b32_e32 v117, 0xffff0000, v171
	v_pk_fma_f32 v[112:113], v[112:113], v[116:117], v[114:115]
	v_lshlrev_b32_e32 v114, 16, v176
	v_and_b32_e32 v115, 0xffff0000, v176
	v_lshlrev_b32_e32 v116, 16, v172
	v_and_b32_e32 v117, 0xffff0000, v172
	v_pk_fma_f32 v[108:109], v[106:107], v[116:117], v[114:115]
	v_add_f32_e32 v106, 1.0, v119
	v_add_f32_e32 v107, 1.0, v120
	v_rcp_f32_e32 v106, v106
	v_rcp_f32_e32 v107, v107
	v_lshlrev_b32_e32 v114, 16, v177
	v_and_b32_e32 v115, 0xffff0000, v177
	v_lshlrev_b32_e32 v116, 16, v173
	v_and_b32_e32 v117, 0xffff0000, v173
	v_pk_fma_f32 v[114:115], v[106:107], v[116:117], v[114:115]
	v_cvt_pk_bf16_f32 v106, v110, v111
	v_mul_f32_e32 v102, v102, v118
	v_mul_f32_e32 v103, v103, v118
	v_cvt_pk_bf16_f32 v107, v112, v113
	v_and_b32_e32 v111, 0xffff0000, v106
	v_mul_f32_e32 v102, 0xbfb8aa3b, v102
	v_mul_f32_e32 v103, 0xbfb8aa3b, v103
	v_mul_f32_e32 v104, v104, v118
	v_mul_f32_e32 v105, v105, v118
	v_lshlrev_b32_e32 v110, 16, v106
	v_and_b32_e32 v113, 0xffff0000, v107
	v_mul_f32_e32 v111, v111, v111
	v_exp_f32_e32 v102, v102
	v_exp_f32_e32 v103, v103
	v_mul_f32_e32 v104, 0xbfb8aa3b, v104
	v_mul_f32_e32 v105, 0xbfb8aa3b, v105
	v_cvt_pk_bf16_f32 v108, v108, v109
	v_lshlrev_b32_e32 v112, 16, v107
	v_fmac_f32_e32 v111, v110, v110
	v_mul_f32_e32 v110, v113, v113
	v_exp_f32_e32 v104, v104
	v_exp_f32_e32 v105, v105
	v_cvt_pk_bf16_f32 v109, v114, v115
	v_and_b32_e32 v115, 0xffff0000, v108
	v_fmac_f32_e32 v110, v112, v112
	v_mul_f32_e32 v98, v98, v118
	v_lshlrev_b32_e32 v114, 16, v108
	v_add_f32_e32 v110, v111, v110
	v_mul_f32_e32 v111, v115, v115
	v_mul_f32_e32 v98, 0xbfb8aa3b, v98
	v_and_b32_e32 v117, 0xffff0000, v109
	v_fmac_f32_e32 v111, v114, v114
	v_add_f32_e32 v102, 1.0, v102
	v_add_f32_e32 v103, 1.0, v103
	v_exp_f32_e32 v115, v98
	v_mul_f32_e32 v98, v99, v118
	v_lshlrev_b32_e32 v116, 16, v109
	v_add_f32_e32 v110, v111, v110
	v_mul_f32_e32 v111, v117, v117
	v_rcp_f32_e32 v102, v102
	v_rcp_f32_e32 v103, v103
	v_add_f32_e32 v104, 1.0, v104
	v_add_f32_e32 v105, 1.0, v105
	v_mul_f32_e32 v98, 0xbfb8aa3b, v98
	v_mul_f32_e32 v100, v100, v118
	v_mul_f32_e32 v101, v101, v118
	v_fmac_f32_e32 v111, v116, v116
	v_rcp_f32_e32 v104, v104
	v_rcp_f32_e32 v105, v105
	v_exp_f32_e32 v116, v98
	v_mul_f32_e32 v100, 0xbfb8aa3b, v100
	v_mul_f32_e32 v101, 0xbfb8aa3b, v101
	v_exp_f32_e32 v100, v100
	v_exp_f32_e32 v101, v101
	v_add_f32_e32 v114, v111, v110
	s_waitcnt vmcnt(12)
	v_lshlrev_b32_e32 v110, 16, v166
	v_and_b32_e32 v111, 0xffff0000, v166
	s_waitcnt vmcnt(11)
	v_lshlrev_b32_e32 v112, 16, v162
	v_and_b32_e32 v113, 0xffff0000, v162
	v_pk_fma_f32 v[102:103], v[102:103], v[112:113], v[110:111]
	v_lshlrev_b32_e32 v110, 16, v167
	v_and_b32_e32 v111, 0xffff0000, v167
	v_lshlrev_b32_e32 v112, 16, v163
	v_and_b32_e32 v113, 0xffff0000, v163
	v_pk_fma_f32 v[98:99], v[104:105], v[112:113], v[110:111]
	v_add_f32_e32 v104, 1.0, v115
	v_add_f32_e32 v105, 1.0, v116
	v_rcp_f32_e32 v104, v104
	v_rcp_f32_e32 v105, v105
	v_add_f32_e32 v100, 1.0, v100
	v_add_f32_e32 v101, 1.0, v101
	v_rcp_f32_e32 v100, v100
	v_rcp_f32_e32 v101, v101
	v_lshlrev_b32_e32 v110, 16, v168
	v_and_b32_e32 v111, 0xffff0000, v168
	v_lshlrev_b32_e32 v112, 16, v164
	v_and_b32_e32 v113, 0xffff0000, v164
	v_pk_fma_f32 v[104:105], v[104:105], v[112:113], v[110:111]
	v_lshlrev_b32_e32 v110, 16, v169
	v_and_b32_e32 v111, 0xffff0000, v169
	v_lshlrev_b32_e32 v112, 16, v165
	v_and_b32_e32 v113, 0xffff0000, v165
	v_pk_fma_f32 v[110:111], v[100:101], v[112:113], v[110:111]
	v_cvt_pk_bf16_f32 v100, v102, v103
	v_cvt_pk_bf16_f32 v101, v98, v99
	v_and_b32_e32 v99, 0xffff0000, v100
	v_lshlrev_b32_e32 v98, 16, v100
	v_mul_f32_e32 v99, v99, v99
	v_cvt_pk_bf16_f32 v102, v104, v105
	v_and_b32_e32 v105, 0xffff0000, v101
	v_fmac_f32_e32 v99, v98, v98
	v_lshlrev_b32_e32 v104, 16, v101
	v_add_f32_e32 v98, v99, v114
	v_mul_f32_e32 v99, v105, v105
	v_cvt_pk_bf16_f32 v103, v110, v111
	v_and_b32_e32 v111, 0xffff0000, v102
	v_fmac_f32_e32 v99, v104, v104
	v_lshlrev_b32_e32 v110, 16, v102
	v_add_f32_e32 v98, v99, v98
	v_mul_f32_e32 v99, v111, v111
	v_and_b32_e32 v113, 0xffff0000, v103
	v_fmac_f32_e32 v99, v110, v110
	v_lshlrev_b32_e32 v112, 16, v103
	v_add_f32_e32 v98, v99, v98
	v_mul_f32_e32 v99, v113, v113
	v_fmac_f32_e32 v99, v112, v112
	v_add_f32_e32 v98, v99, v98
	ds_bpermute_b32 v99, v229, v98
	v_lshlrev_b64 v[104:105], 11, v[224:225]
	v_lshl_add_u64 v[104:105], s[92:93], 0, v[104:105]
	v_lshl_add_u64 v[104:105], v[204:205], 1, v[104:105]
	global_store_dwordx4 v[104:105], v[106:109], off
	global_store_dwordx4 v[104:105], v[100:103], off offset:256
	s_waitcnt lgkmcnt(0)
	v_add_f32_e32 v98, v98, v99
	ds_bpermute_b32 v99, v228, v98
	s_and_saveexec_b64 s[10:11], vcc
	s_cbranch_execz .LBB0_952
	s_lshl_b32 s20, s82, 2
	v_lshl_add_u64 v[100:101], s[4:5], 0, v[222:223]
	s_ashr_i32 s21, s20, 31
	v_lshl_add_u64 v[100:101], s[20:21], 2, v[100:101]
	s_lshl_b32 s76, s19, 2
	v_lshl_add_u64 v[100:101], v[100:101], 0, s[76:77]
	s_waitcnt lgkmcnt(0)
	v_add_f32_e32 v98, v98, v99
	global_store_dword v[100:101], v98, off
.LBB0_952:
	s_or_b64 exec, exec, s[10:11]
	v_add_f32_e32 v98, v232, v233
	v_fmamk_f32 v98, v98, 0x3a800000, v240
	v_rsq_f32_e32 v102, v98
	s_waitcnt vmcnt(12)
	v_lshlrev_b32_e32 v100, 16, v154
	v_and_b32_e32 v101, 0xffff0000, v154
	v_mul_f32_e32 v94, v94, v102
	v_mul_f32_e32 v95, v95, v102
	v_mul_f32_e32 v94, 0xbfb8aa3b, v94
	v_mul_f32_e32 v95, 0xbfb8aa3b, v95
	v_mul_f32_e32 v96, v96, v102
	v_mul_f32_e32 v97, v97, v102
	v_exp_f32_e32 v98, v94
	v_exp_f32_e32 v95, v95
	v_mul_f32_e32 v96, 0xbfb8aa3b, v96
	v_mul_f32_e32 v97, 0xbfb8aa3b, v97
	v_mul_f32_e32 v90, v90, v102
	v_mul_f32_e32 v91, v91, v102
	v_exp_f32_e32 v96, v96
	v_exp_f32_e32 v97, v97
	v_mul_f32_e32 v90, 0xbfb8aa3b, v90
	v_mul_f32_e32 v91, 0xbfb8aa3b, v91
	v_exp_f32_e32 v90, v90
	v_exp_f32_e32 v91, v91
	v_mul_f32_e32 v92, v92, v102
	v_add_f32_e32 v98, 1.0, v98
	v_add_f32_e32 v95, 1.0, v95
	v_mul_f32_e32 v92, 0xbfb8aa3b, v92
	v_rcp_f32_e32 v98, v98
	s_waitcnt lgkmcnt(0)
	v_rcp_f32_e32 v99, v95
	v_add_f32_e32 v96, 1.0, v96
	v_add_f32_e32 v97, 1.0, v97
	v_exp_f32_e32 v103, v92
	v_mul_f32_e32 v92, v93, v102
	v_rcp_f32_e32 v96, v96
	v_rcp_f32_e32 v97, v97
	v_add_f32_e32 v90, 1.0, v90
	v_add_f32_e32 v91, 1.0, v91
	v_mul_f32_e32 v92, 0xbfb8aa3b, v92
	v_rcp_f32_e32 v90, v90
	v_rcp_f32_e32 v91, v91
	v_exp_f32_e32 v104, v92
	v_lshlrev_b32_e32 v94, 16, v158
	v_and_b32_e32 v95, 0xffff0000, v158
	v_pk_fma_f32 v[94:95], v[98:99], v[100:101], v[94:95]
	v_lshlrev_b32_e32 v98, 16, v159
	v_and_b32_e32 v99, 0xffff0000, v159
	v_lshlrev_b32_e32 v100, 16, v155
	v_and_b32_e32 v101, 0xffff0000, v155
	v_pk_fma_f32 v[96:97], v[96:97], v[100:101], v[98:99]
	v_lshlrev_b32_e32 v98, 16, v160
	v_and_b32_e32 v99, 0xffff0000, v160
	v_lshlrev_b32_e32 v100, 16, v156
	v_and_b32_e32 v101, 0xffff0000, v156
	v_pk_fma_f32 v[92:93], v[90:91], v[100:101], v[98:99]
	v_add_f32_e32 v90, 1.0, v103
	v_add_f32_e32 v91, 1.0, v104
	v_rcp_f32_e32 v90, v90
	v_rcp_f32_e32 v91, v91
	v_lshlrev_b32_e32 v98, 16, v161
	v_and_b32_e32 v99, 0xffff0000, v161
	v_lshlrev_b32_e32 v100, 16, v157
	v_and_b32_e32 v101, 0xffff0000, v157
	v_pk_fma_f32 v[98:99], v[90:91], v[100:101], v[98:99]
	v_cvt_pk_bf16_f32 v90, v94, v95
	v_mul_f32_e32 v86, v86, v102
	v_mul_f32_e32 v87, v87, v102
	v_cvt_pk_bf16_f32 v91, v96, v97
	v_and_b32_e32 v95, 0xffff0000, v90
	v_mul_f32_e32 v86, 0xbfb8aa3b, v86
	v_mul_f32_e32 v87, 0xbfb8aa3b, v87
	v_mul_f32_e32 v88, v88, v102
	v_mul_f32_e32 v89, v89, v102
	v_lshlrev_b32_e32 v94, 16, v90
	v_and_b32_e32 v97, 0xffff0000, v91
	v_mul_f32_e32 v95, v95, v95
	v_exp_f32_e32 v86, v86
	v_exp_f32_e32 v87, v87
	v_mul_f32_e32 v88, 0xbfb8aa3b, v88
	v_mul_f32_e32 v89, 0xbfb8aa3b, v89
	v_cvt_pk_bf16_f32 v92, v92, v93
	v_lshlrev_b32_e32 v96, 16, v91
	v_fmac_f32_e32 v95, v94, v94
	v_mul_f32_e32 v94, v97, v97
	v_exp_f32_e32 v88, v88
	v_exp_f32_e32 v89, v89
	v_cvt_pk_bf16_f32 v93, v98, v99
	v_and_b32_e32 v99, 0xffff0000, v92
	v_fmac_f32_e32 v94, v96, v96
	v_mul_f32_e32 v82, v82, v102
	v_lshlrev_b32_e32 v98, 16, v92
	v_add_f32_e32 v94, v95, v94
	v_mul_f32_e32 v95, v99, v99
	v_mul_f32_e32 v82, 0xbfb8aa3b, v82
	v_and_b32_e32 v101, 0xffff0000, v93
	v_fmac_f32_e32 v95, v98, v98
	v_add_f32_e32 v86, 1.0, v86
	v_add_f32_e32 v87, 1.0, v87
	v_exp_f32_e32 v99, v82
	v_mul_f32_e32 v82, v83, v102
	v_lshlrev_b32_e32 v100, 16, v93
	v_add_f32_e32 v94, v95, v94
	v_mul_f32_e32 v95, v101, v101
	v_rcp_f32_e32 v86, v86
	v_rcp_f32_e32 v87, v87
	v_add_f32_e32 v88, 1.0, v88
	v_add_f32_e32 v89, 1.0, v89
	v_mul_f32_e32 v82, 0xbfb8aa3b, v82
	v_mul_f32_e32 v84, v84, v102
	v_mul_f32_e32 v85, v85, v102
	v_fmac_f32_e32 v95, v100, v100
	v_rcp_f32_e32 v88, v88
	v_rcp_f32_e32 v89, v89
	v_exp_f32_e32 v100, v82
	v_mul_f32_e32 v84, 0xbfb8aa3b, v84
	v_mul_f32_e32 v85, 0xbfb8aa3b, v85
	v_exp_f32_e32 v84, v84
	v_exp_f32_e32 v85, v85
	v_add_f32_e32 v98, v95, v94
	s_waitcnt vmcnt(11)
	v_lshlrev_b32_e32 v94, 16, v146
	v_and_b32_e32 v95, 0xffff0000, v146
	s_waitcnt vmcnt(10)
	v_lshlrev_b32_e32 v96, 16, v142
	v_and_b32_e32 v97, 0xffff0000, v142
	v_pk_fma_f32 v[86:87], v[86:87], v[96:97], v[94:95]
	v_lshlrev_b32_e32 v94, 16, v147
	v_and_b32_e32 v95, 0xffff0000, v147
	v_lshlrev_b32_e32 v96, 16, v143
	v_and_b32_e32 v97, 0xffff0000, v143
	v_pk_fma_f32 v[82:83], v[88:89], v[96:97], v[94:95]
	v_add_f32_e32 v88, 1.0, v99
	v_add_f32_e32 v89, 1.0, v100
	v_rcp_f32_e32 v88, v88
	v_rcp_f32_e32 v89, v89
	v_add_f32_e32 v84, 1.0, v84
	v_add_f32_e32 v85, 1.0, v85
	v_rcp_f32_e32 v84, v84
	v_rcp_f32_e32 v85, v85
	v_lshlrev_b32_e32 v94, 16, v148
	v_and_b32_e32 v95, 0xffff0000, v148
	v_lshlrev_b32_e32 v96, 16, v144
	v_and_b32_e32 v97, 0xffff0000, v144
	v_pk_fma_f32 v[88:89], v[88:89], v[96:97], v[94:95]
	v_lshlrev_b32_e32 v94, 16, v149
	v_and_b32_e32 v95, 0xffff0000, v149
	v_lshlrev_b32_e32 v96, 16, v145
	v_and_b32_e32 v97, 0xffff0000, v145
	v_pk_fma_f32 v[94:95], v[84:85], v[96:97], v[94:95]
	v_cvt_pk_bf16_f32 v84, v86, v87
	v_cvt_pk_bf16_f32 v85, v82, v83
	v_and_b32_e32 v83, 0xffff0000, v84
	v_lshlrev_b32_e32 v82, 16, v84
	v_mul_f32_e32 v83, v83, v83
	v_cvt_pk_bf16_f32 v86, v88, v89
	v_and_b32_e32 v89, 0xffff0000, v85
	v_fmac_f32_e32 v83, v82, v82
	v_lshlrev_b32_e32 v88, 16, v85
	v_add_f32_e32 v82, v83, v98
	v_mul_f32_e32 v83, v89, v89
	v_cvt_pk_bf16_f32 v87, v94, v95
	v_and_b32_e32 v95, 0xffff0000, v86
	v_fmac_f32_e32 v83, v88, v88
	v_lshlrev_b32_e32 v94, 16, v86
	v_add_f32_e32 v82, v83, v82
	v_mul_f32_e32 v83, v95, v95
	v_and_b32_e32 v97, 0xffff0000, v87
	v_fmac_f32_e32 v83, v94, v94
	v_lshlrev_b32_e32 v96, 16, v87
	v_add_f32_e32 v82, v83, v82
	v_mul_f32_e32 v83, v97, v97
	v_fmac_f32_e32 v83, v96, v96
	v_add_f32_e32 v82, v83, v82
	ds_bpermute_b32 v83, v229, v82
	v_lshlrev_b64 v[88:89], 11, v[218:219]
	v_lshl_add_u64 v[88:89], s[92:93], 0, v[88:89]
	v_lshl_add_u64 v[88:89], v[204:205], 1, v[88:89]
	global_store_dwordx4 v[88:89], v[90:93], off
	global_store_dwordx4 v[88:89], v[84:87], off offset:256
	s_waitcnt lgkmcnt(0)
	v_add_f32_e32 v82, v82, v83
	ds_bpermute_b32 v83, v228, v82
	s_and_saveexec_b64 s[10:11], vcc
	s_cbranch_execz .LBB0_954
	s_lshl_b32 s20, s82, 2
	v_lshl_add_u64 v[84:85], s[4:5], 0, v[220:221]
	s_ashr_i32 s21, s20, 31
	v_lshl_add_u64 v[84:85], s[20:21], 2, v[84:85]
	s_lshl_b32 s76, s19, 2
	v_lshl_add_u64 v[84:85], v[84:85], 0, s[76:77]
	s_waitcnt lgkmcnt(0)
	v_add_f32_e32 v82, v82, v83
	global_store_dword v[84:85], v82, off
.LBB0_954:
	s_or_b64 exec, exec, s[10:11]
	v_add_f32_e32 v82, v230, v231
	v_fmamk_f32 v82, v82, 0x3a800000, v240
	v_rsq_f32_e32 v86, v82
	s_waitcnt vmcnt(11)
	v_lshlrev_b32_e32 v84, 16, v134
	v_and_b32_e32 v85, 0xffff0000, v134
	v_mul_f32_e32 v78, v78, v86
	v_mul_f32_e32 v79, v79, v86
	v_mul_f32_e32 v78, 0xbfb8aa3b, v78
	v_mul_f32_e32 v79, 0xbfb8aa3b, v79
	v_mul_f32_e32 v80, v80, v86
	v_mul_f32_e32 v81, v81, v86
	v_exp_f32_e32 v82, v78
	v_exp_f32_e32 v79, v79
	v_mul_f32_e32 v80, 0xbfb8aa3b, v80
	v_mul_f32_e32 v81, 0xbfb8aa3b, v81
	v_mul_f32_e32 v74, v74, v86
	v_mul_f32_e32 v75, v75, v86
	v_exp_f32_e32 v80, v80
	v_exp_f32_e32 v81, v81
	v_mul_f32_e32 v74, 0xbfb8aa3b, v74
	v_mul_f32_e32 v75, 0xbfb8aa3b, v75
	v_exp_f32_e32 v74, v74
	v_exp_f32_e32 v75, v75
	v_mul_f32_e32 v76, v76, v86
	v_add_f32_e32 v82, 1.0, v82
	v_add_f32_e32 v79, 1.0, v79
	v_mul_f32_e32 v76, 0xbfb8aa3b, v76
	v_rcp_f32_e32 v82, v82
	s_waitcnt lgkmcnt(0)
	v_rcp_f32_e32 v83, v79
	v_add_f32_e32 v80, 1.0, v80
	v_add_f32_e32 v81, 1.0, v81
	v_exp_f32_e32 v87, v76
	v_mul_f32_e32 v76, v77, v86
	v_rcp_f32_e32 v80, v80
	v_rcp_f32_e32 v81, v81
	v_add_f32_e32 v74, 1.0, v74
	v_add_f32_e32 v75, 1.0, v75
	v_mul_f32_e32 v76, 0xbfb8aa3b, v76
	v_rcp_f32_e32 v74, v74
	v_rcp_f32_e32 v75, v75
	v_exp_f32_e32 v88, v76
	v_lshlrev_b32_e32 v78, 16, v138
	v_and_b32_e32 v79, 0xffff0000, v138
	v_pk_fma_f32 v[78:79], v[82:83], v[84:85], v[78:79]
	v_lshlrev_b32_e32 v82, 16, v139
	v_and_b32_e32 v83, 0xffff0000, v139
	v_lshlrev_b32_e32 v84, 16, v135
	v_and_b32_e32 v85, 0xffff0000, v135
	v_pk_fma_f32 v[80:81], v[80:81], v[84:85], v[82:83]
	v_lshlrev_b32_e32 v82, 16, v140
	v_and_b32_e32 v83, 0xffff0000, v140
	v_lshlrev_b32_e32 v84, 16, v136
	v_and_b32_e32 v85, 0xffff0000, v136
	v_pk_fma_f32 v[76:77], v[74:75], v[84:85], v[82:83]
	v_add_f32_e32 v74, 1.0, v87
	v_add_f32_e32 v75, 1.0, v88
	v_rcp_f32_e32 v74, v74
	v_rcp_f32_e32 v75, v75
	v_lshlrev_b32_e32 v82, 16, v141
	v_and_b32_e32 v83, 0xffff0000, v141
	v_lshlrev_b32_e32 v84, 16, v137
	v_and_b32_e32 v85, 0xffff0000, v137
	v_pk_fma_f32 v[82:83], v[74:75], v[84:85], v[82:83]
	v_cvt_pk_bf16_f32 v74, v78, v79
	v_mul_f32_e32 v70, v70, v86
	v_mul_f32_e32 v71, v71, v86
	v_cvt_pk_bf16_f32 v75, v80, v81
	v_and_b32_e32 v79, 0xffff0000, v74
	v_mul_f32_e32 v70, 0xbfb8aa3b, v70
	v_mul_f32_e32 v71, 0xbfb8aa3b, v71
	v_mul_f32_e32 v72, v72, v86
	v_mul_f32_e32 v73, v73, v86
	v_lshlrev_b32_e32 v78, 16, v74
	v_and_b32_e32 v81, 0xffff0000, v75
	v_mul_f32_e32 v79, v79, v79
	v_exp_f32_e32 v70, v70
	v_exp_f32_e32 v71, v71
	v_mul_f32_e32 v72, 0xbfb8aa3b, v72
	v_mul_f32_e32 v73, 0xbfb8aa3b, v73
	v_cvt_pk_bf16_f32 v76, v76, v77
	v_lshlrev_b32_e32 v80, 16, v75
	v_fmac_f32_e32 v79, v78, v78
	v_mul_f32_e32 v78, v81, v81
	v_exp_f32_e32 v72, v72
	v_exp_f32_e32 v73, v73
	v_cvt_pk_bf16_f32 v77, v82, v83
	v_and_b32_e32 v83, 0xffff0000, v76
	v_fmac_f32_e32 v78, v80, v80
	v_mul_f32_e32 v66, v66, v86
	v_lshlrev_b32_e32 v82, 16, v76
	v_add_f32_e32 v78, v79, v78
	v_mul_f32_e32 v79, v83, v83
	v_mul_f32_e32 v66, 0xbfb8aa3b, v66
	v_and_b32_e32 v85, 0xffff0000, v77
	v_fmac_f32_e32 v79, v82, v82
	v_add_f32_e32 v70, 1.0, v70
	v_add_f32_e32 v71, 1.0, v71
	v_exp_f32_e32 v83, v66
	v_mul_f32_e32 v66, v67, v86
	v_lshlrev_b32_e32 v84, 16, v77
	v_add_f32_e32 v78, v79, v78
	v_mul_f32_e32 v79, v85, v85
	v_rcp_f32_e32 v70, v70
	v_rcp_f32_e32 v71, v71
	v_add_f32_e32 v72, 1.0, v72
	v_add_f32_e32 v73, 1.0, v73
	v_mul_f32_e32 v66, 0xbfb8aa3b, v66
	v_mul_f32_e32 v68, v68, v86
	v_mul_f32_e32 v69, v69, v86
	v_fmac_f32_e32 v79, v84, v84
	v_rcp_f32_e32 v72, v72
	v_rcp_f32_e32 v73, v73
	v_exp_f32_e32 v84, v66
	v_mul_f32_e32 v68, 0xbfb8aa3b, v68
	v_mul_f32_e32 v69, 0xbfb8aa3b, v69
	v_exp_f32_e32 v68, v68
	v_exp_f32_e32 v69, v69
	v_add_f32_e32 v82, v79, v78
	s_waitcnt vmcnt(10)
	v_lshlrev_b32_e32 v78, 16, v126
	v_and_b32_e32 v79, 0xffff0000, v126
	s_waitcnt vmcnt(9)
	v_lshlrev_b32_e32 v80, 16, v122
	v_and_b32_e32 v81, 0xffff0000, v122
	v_pk_fma_f32 v[70:71], v[70:71], v[80:81], v[78:79]
	v_lshlrev_b32_e32 v78, 16, v127
	v_and_b32_e32 v79, 0xffff0000, v127
	v_lshlrev_b32_e32 v80, 16, v123
	v_and_b32_e32 v81, 0xffff0000, v123
	v_pk_fma_f32 v[66:67], v[72:73], v[80:81], v[78:79]
	v_add_f32_e32 v72, 1.0, v83
	v_add_f32_e32 v73, 1.0, v84
	v_rcp_f32_e32 v72, v72
	v_rcp_f32_e32 v73, v73
	v_add_f32_e32 v68, 1.0, v68
	v_add_f32_e32 v69, 1.0, v69
	v_rcp_f32_e32 v68, v68
	v_rcp_f32_e32 v69, v69
	v_lshlrev_b32_e32 v78, 16, v128
	v_and_b32_e32 v79, 0xffff0000, v128
	v_lshlrev_b32_e32 v80, 16, v124
	v_and_b32_e32 v81, 0xffff0000, v124
	v_pk_fma_f32 v[72:73], v[72:73], v[80:81], v[78:79]
	v_lshlrev_b32_e32 v78, 16, v129
	v_and_b32_e32 v79, 0xffff0000, v129
	v_lshlrev_b32_e32 v80, 16, v125
	v_and_b32_e32 v81, 0xffff0000, v125
	v_pk_fma_f32 v[78:79], v[68:69], v[80:81], v[78:79]
	v_cvt_pk_bf16_f32 v68, v70, v71
	v_cvt_pk_bf16_f32 v69, v66, v67
	v_and_b32_e32 v67, 0xffff0000, v68
	v_lshlrev_b32_e32 v66, 16, v68
	v_mul_f32_e32 v67, v67, v67
	v_cvt_pk_bf16_f32 v70, v72, v73
	v_and_b32_e32 v73, 0xffff0000, v69
	v_fmac_f32_e32 v67, v66, v66
	v_lshlrev_b32_e32 v72, 16, v69
	v_add_f32_e32 v66, v67, v82
	v_mul_f32_e32 v67, v73, v73
	v_cvt_pk_bf16_f32 v71, v78, v79
	v_and_b32_e32 v79, 0xffff0000, v70
	v_fmac_f32_e32 v67, v72, v72
	v_lshlrev_b32_e32 v78, 16, v70
	v_add_f32_e32 v66, v67, v66
	v_mul_f32_e32 v67, v79, v79
	v_and_b32_e32 v81, 0xffff0000, v71
	v_fmac_f32_e32 v67, v78, v78
	v_lshlrev_b32_e32 v80, 16, v71
	v_add_f32_e32 v66, v67, v66
	v_mul_f32_e32 v67, v81, v81
	v_fmac_f32_e32 v67, v80, v80
	v_add_f32_e32 v66, v67, v66
	ds_bpermute_b32 v67, v229, v66
	v_lshlrev_b64 v[72:73], 11, v[214:215]
	v_lshl_add_u64 v[72:73], s[92:93], 0, v[72:73]
	v_lshl_add_u64 v[72:73], v[204:205], 1, v[72:73]
	global_store_dwordx4 v[72:73], v[74:77], off
	global_store_dwordx4 v[72:73], v[68:71], off offset:256
	s_waitcnt lgkmcnt(0)
	v_add_f32_e32 v66, v66, v67
	ds_bpermute_b32 v67, v228, v66
	s_and_saveexec_b64 s[10:11], vcc
	s_cbranch_execz .LBB0_956
	s_lshl_b32 s20, s82, 2
	v_lshl_add_u64 v[68:69], s[4:5], 0, v[216:217]
	s_ashr_i32 s21, s20, 31
	v_lshl_add_u64 v[68:69], s[20:21], 2, v[68:69]
	s_lshl_b32 s76, s19, 2
	v_lshl_add_u64 v[68:69], v[68:69], 0, s[76:77]
	s_waitcnt lgkmcnt(0)
	v_add_f32_e32 v66, v66, v67
	global_store_dword v[68:69], v66, off
.LBB0_956:
	s_or_b64 exec, exec, s[10:11]
	v_add_u32_e32 v144, 0x80, v208
	v_ashrrev_i32_e32 v145, 31, v144
	s_waitcnt lgkmcnt(0)
	v_lshlrev_b64 v[66:67], 10, v[144:145]
	v_lshl_add_u64 v[66:67], v[66:67], 0, v[204:205]
	v_lshlrev_b64 v[66:67], 1, v[66:67]
	v_lshl_add_u64 v[68:69], s[88:89], 0, v[66:67]
	v_lshl_add_u64 v[66:67], s[62:63], 0, v[66:67]
	v_lshlrev_b64 v[142:143], 6, v[144:145]
	v_add_u32_e32 v140, 0x90, v208
	v_ashrrev_i32_e32 v141, 31, v140
	v_lshlrev_b64 v[138:139], 6, v[140:141]
	v_add_u32_e32 v134, 0xa0, v208
	v_ashrrev_i32_e32 v135, 31, v134
	v_lshlrev_b64 v[136:137], 6, v[134:135]
	v_add_u32_e32 v130, 0xb0, v208
	v_ashrrev_i32_e32 v131, 31, v130
	v_lshlrev_b64 v[132:133], 6, v[130:131]
	v_lshl_add_u64 v[146:147], v[206:207], 0, v[132:133]
	v_lshlrev_b64 v[144:145], 11, v[144:145]
	v_lshl_add_u64 v[246:247], v[206:207], 0, v[142:143]
	v_lshl_add_u64 v[248:249], v[206:207], 0, v[138:139]
	global_load_dwordx4 v[78:81], v[246:247], off
	global_load_dwordx4 v[74:77], v[248:249], off
	v_lshl_add_u64 v[246:247], v[206:207], 0, v[136:137]
	global_load_dwordx4 v[70:73], v[246:247], off
	global_load_dwordx4 v[154:157], v[146:147], off
	global_load_dwordx4 v[126:129], v[68:69], off
	global_load_dwordx4 v[122:125], v[66:67], off
	global_load_dwordx4 v[118:121], v[68:69], off offset:256
	global_load_dwordx4 v[114:117], v[66:67], off offset:256
	v_lshlrev_b64 v[66:67], 10, v[140:141]
	v_lshl_add_u64 v[66:67], v[66:67], 0, v[204:205]
	v_lshlrev_b64 v[66:67], 1, v[66:67]
	v_lshl_add_u64 v[68:69], s[88:89], 0, v[66:67]
	v_lshl_add_u64 v[66:67], s[62:63], 0, v[66:67]
	global_load_dwordx4 v[110:113], v[68:69], off
	global_load_dwordx4 v[106:109], v[66:67], off
	global_load_dwordx4 v[102:105], v[68:69], off offset:256
	global_load_dwordx4 v[98:101], v[66:67], off offset:256
	v_lshlrev_b64 v[66:67], 10, v[134:135]
	v_lshl_add_u64 v[66:67], v[66:67], 0, v[204:205]
	v_lshlrev_b64 v[66:67], 1, v[66:67]
	v_lshl_add_u64 v[68:69], s[88:89], 0, v[66:67]
	v_lshl_add_u64 v[66:67], s[62:63], 0, v[66:67]
	global_load_dwordx4 v[94:97], v[68:69], off
	global_load_dwordx4 v[90:93], v[66:67], off
	global_load_dwordx4 v[86:89], v[68:69], off offset:256
	global_load_dwordx4 v[82:85], v[66:67], off offset:256
	s_waitcnt vmcnt(12)
	v_add_f32_e32 v78, v78, v79
	v_add_f32_e32 v79, v80, v81
	v_add_f32_e32 v74, v74, v75
	v_add_f32_e32 v75, v76, v77
	v_add_f32_e32 v70, v70, v71
	v_add_f32_e32 v71, v72, v73
	v_add_f32_e32 v78, v78, v79
	v_add_f32_e32 v74, v74, v75
	v_add_f32_e32 v70, v70, v71
	ds_bpermute_b32 v79, v229, v78
	ds_bpermute_b32 v75, v229, v74
	ds_bpermute_b32 v71, v229, v70
	s_waitcnt lgkmcnt(2)
	v_add_f32_e32 v78, v78, v79
	ds_bpermute_b32 v79, v228, v78
	s_waitcnt lgkmcnt(2)
	v_add_f32_e32 v150, v74, v75
	ds_bpermute_b32 v151, v228, v150
	s_waitcnt lgkmcnt(2)
	v_add_f32_e32 v148, v70, v71
	ds_bpermute_b32 v149, v228, v148
	s_waitcnt lgkmcnt(2)
	v_add_f32_e32 v78, v78, v79
	v_fmamk_f32 v78, v78, 0x3a800000, v240
	v_rsq_f32_e32 v152, v78
	v_lshlrev_b64 v[66:67], 10, v[130:131]
	v_lshl_add_u64 v[66:67], v[66:67], 0, v[204:205]
	v_lshlrev_b64 v[66:67], 1, v[66:67]
	v_lshl_add_u64 v[68:69], s[88:89], 0, v[66:67]
	v_lshl_add_u64 v[66:67], s[62:63], 0, v[66:67]
	global_load_dwordx4 v[78:81], v[68:69], off
	global_load_dwordx4 v[74:77], v[66:67], off
	global_load_dwordx4 v[70:73], v[68:69], off offset:256
	s_nop 0
	global_load_dwordx4 v[66:69], v[66:67], off offset:256
	v_mul_f32_e32 v64, v64, v152
	v_mul_f32_e32 v65, v65, v152
	v_mul_f32_e32 v64, 0xbfb8aa3b, v64
	v_mul_f32_e32 v65, 0xbfb8aa3b, v65
	v_mul_f32_e32 v58, v58, v152
	v_mul_f32_e32 v59, v59, v152
	v_exp_f32_e32 v64, v64
	v_exp_f32_e32 v65, v65
	v_mul_f32_e32 v58, 0xbfb8aa3b, v58
	v_mul_f32_e32 v59, 0xbfb8aa3b, v59
	v_exp_f32_e32 v58, v58
	v_exp_f32_e32 v59, v59
	v_add_f32_e32 v64, 1.0, v64
	v_add_f32_e32 v65, 1.0, v65
	v_rcp_f32_e32 v64, v64
	v_rcp_f32_e32 v65, v65
	v_add_f32_e32 v58, 1.0, v58
	v_add_f32_e32 v59, 1.0, v59
	v_rcp_f32_e32 v58, v58
	v_rcp_f32_e32 v59, v59
	v_mul_f32_e32 v62, v62, v152
	v_mul_f32_e32 v63, v63, v152
	v_mul_f32_e32 v62, 0xbfb8aa3b, v62
	v_mul_f32_e32 v63, 0xbfb8aa3b, v63
	v_exp_f32_e32 v62, v62
	v_exp_f32_e32 v63, v63
	v_mul_f32_e32 v54, v54, v152
	v_mul_f32_e32 v55, v55, v152
	v_add_f32_e32 v62, 1.0, v62
	v_add_f32_e32 v63, 1.0, v63
	v_rcp_f32_e32 v62, v62
	v_rcp_f32_e32 v63, v63
	v_mul_f32_e32 v54, 0xbfb8aa3b, v54
	v_mul_f32_e32 v55, 0xbfb8aa3b, v55
	v_mul_f32_e32 v56, v56, v152
	v_mul_f32_e32 v57, v57, v152
	v_exp_f32_e32 v54, v54
	v_exp_f32_e32 v55, v55
	v_mul_f32_e32 v56, 0xbfb8aa3b, v56
	v_mul_f32_e32 v57, 0xbfb8aa3b, v57
	v_mul_f32_e32 v50, v50, v152
	v_mul_f32_e32 v51, v51, v152
	v_exp_f32_e32 v56, v56
	v_exp_f32_e32 v57, v57
	v_mul_f32_e32 v50, 0xbfb8aa3b, v50
	v_mul_f32_e32 v51, 0xbfb8aa3b, v51
	v_exp_f32_e32 v50, v50
	v_exp_f32_e32 v51, v51
	v_add_f32_e32 v54, 1.0, v54
	v_add_f32_e32 v55, 1.0, v55
	v_rcp_f32_e32 v54, v54
	v_rcp_f32_e32 v55, v55
	v_add_f32_e32 v56, 1.0, v56
	v_add_f32_e32 v57, 1.0, v57
	v_rcp_f32_e32 v56, v56
	v_rcp_f32_e32 v57, v57
	v_add_f32_e32 v50, 1.0, v50
	v_add_f32_e32 v51, 1.0, v51
	v_rcp_f32_e32 v50, v50
	v_rcp_f32_e32 v51, v51
	v_add_f32_e32 v146, v154, v155
	v_add_f32_e32 v147, v156, v157
	s_waitcnt vmcnt(15)
	v_lshlrev_b32_e32 v154, 16, v126
	v_and_b32_e32 v155, 0xffff0000, v126
	s_waitcnt vmcnt(14)
	v_lshlrev_b32_e32 v156, 16, v122
	v_and_b32_e32 v157, 0xffff0000, v122
	v_lshlrev_b32_e32 v126, 16, v127
	v_and_b32_e32 v127, 0xffff0000, v127
	v_lshlrev_b32_e32 v122, 16, v123
	v_and_b32_e32 v123, 0xffff0000, v123
	v_pk_fma_f32 v[64:65], v[64:65], v[122:123], v[126:127]
	v_lshlrev_b32_e32 v122, 16, v128
	v_and_b32_e32 v123, 0xffff0000, v128
	v_lshlrev_b32_e32 v126, 16, v124
	v_and_b32_e32 v127, 0xffff0000, v124
	v_pk_fma_f32 v[122:123], v[58:59], v[126:127], v[122:123]
	v_mul_f32_e32 v58, v60, v152
	v_mul_f32_e32 v59, v61, v152
	v_mul_f32_e32 v58, 0xbfb8aa3b, v58
	v_mul_f32_e32 v59, 0xbfb8aa3b, v59
	v_exp_f32_e32 v58, v58
	v_exp_f32_e32 v59, v59
	v_pk_fma_f32 v[62:63], v[62:63], v[156:157], v[154:155]
	v_lshlrev_b32_e32 v60, 16, v129
	v_add_f32_e32 v58, 1.0, v58
	v_add_f32_e32 v59, 1.0, v59
	v_rcp_f32_e32 v58, v58
	v_rcp_f32_e32 v59, v59
	v_and_b32_e32 v61, 0xffff0000, v129
	v_lshlrev_b32_e32 v124, 16, v125
	v_and_b32_e32 v125, 0xffff0000, v125
	v_pk_fma_f32 v[124:125], v[58:59], v[124:125], v[60:61]
	v_cvt_pk_bf16_f32 v58, v62, v63
	v_lshl_add_u64 v[62:63], s[92:93], 0, v[144:145]
	v_cvt_pk_bf16_f32 v59, v64, v65
	v_cvt_pk_bf16_f32 v60, v122, v123
	v_cvt_pk_bf16_f32 v61, v124, v125
	v_lshl_add_u64 v[62:63], v[204:205], 1, v[62:63]
	global_store_dwordx4 v[62:63], v[58:61], off
	v_lshlrev_b32_e32 v64, 16, v58
	v_lshlrev_b32_e32 v65, 16, v59
	v_and_b32_e32 v58, 0xffff0000, v58
	v_and_b32_e32 v59, 0xffff0000, v59
	v_mul_f32_e32 v58, v58, v58
	v_mul_f32_e32 v59, v59, v59
	v_lshlrev_b32_e32 v122, 16, v60
	v_and_b32_e32 v60, 0xffff0000, v60
	v_fmac_f32_e32 v58, v64, v64
	v_fmac_f32_e32 v59, v65, v65
	v_add_f32_e32 v58, v58, v59
	v_mul_f32_e32 v59, v60, v60
	v_lshlrev_b32_e32 v123, 16, v61
	v_and_b32_e32 v61, 0xffff0000, v61
	v_fmac_f32_e32 v59, v122, v122
	v_add_f32_e32 v58, v59, v58
	v_mul_f32_e32 v59, v61, v61
	v_fmac_f32_e32 v59, v123, v123
	v_add_f32_e32 v64, v59, v58
	s_waitcnt vmcnt(14)
	v_lshlrev_b32_e32 v58, 16, v118
	v_and_b32_e32 v59, 0xffff0000, v118
	s_waitcnt vmcnt(13)
	v_lshlrev_b32_e32 v60, 16, v114
	v_and_b32_e32 v61, 0xffff0000, v114
	v_pk_fma_f32 v[54:55], v[54:55], v[60:61], v[58:59]
	v_lshlrev_b32_e32 v58, 16, v119
	v_and_b32_e32 v59, 0xffff0000, v119
	v_lshlrev_b32_e32 v60, 16, v115
	v_and_b32_e32 v61, 0xffff0000, v115
	v_pk_fma_f32 v[56:57], v[56:57], v[60:61], v[58:59]
	v_lshlrev_b32_e32 v58, 16, v120
	v_and_b32_e32 v59, 0xffff0000, v120
	v_lshlrev_b32_e32 v60, 16, v116
	v_and_b32_e32 v61, 0xffff0000, v116
	v_pk_fma_f32 v[58:59], v[50:51], v[60:61], v[58:59]
	v_mul_f32_e32 v50, v52, v152
	v_mul_f32_e32 v51, v53, v152
	v_mul_f32_e32 v50, 0xbfb8aa3b, v50
	v_mul_f32_e32 v51, 0xbfb8aa3b, v51
	v_exp_f32_e32 v50, v50
	v_exp_f32_e32 v51, v51
	v_lshlrev_b32_e32 v52, 16, v121
	v_and_b32_e32 v53, 0xffff0000, v121
	v_add_f32_e32 v50, 1.0, v50
	v_add_f32_e32 v51, 1.0, v51
	v_rcp_f32_e32 v50, v50
	v_rcp_f32_e32 v51, v51
	v_lshlrev_b32_e32 v60, 16, v117
	v_and_b32_e32 v61, 0xffff0000, v117
	v_add_f32_e32 v146, v146, v147
	v_pk_fma_f32 v[60:61], v[50:51], v[60:61], v[52:53]
	v_cvt_pk_bf16_f32 v50, v54, v55
	v_cvt_pk_bf16_f32 v51, v56, v57
	v_cvt_pk_bf16_f32 v52, v58, v59
	v_cvt_pk_bf16_f32 v53, v60, v61
	global_store_dwordx4 v[62:63], v[50:53], off offset:256
	v_lshlrev_b32_e32 v54, 16, v50
	v_lshlrev_b32_e32 v55, 16, v51
	v_and_b32_e32 v50, 0xffff0000, v50
	v_and_b32_e32 v51, 0xffff0000, v51
	v_mul_f32_e32 v50, v50, v50
	v_fmac_f32_e32 v50, v54, v54
	v_mul_f32_e32 v51, v51, v51
	v_lshlrev_b32_e32 v56, 16, v52
	v_and_b32_e32 v52, 0xffff0000, v52
	v_add_f32_e32 v50, v50, v64
	v_fmac_f32_e32 v51, v55, v55
	v_add_f32_e32 v50, v51, v50
	v_mul_f32_e32 v51, v52, v52
	v_lshlrev_b32_e32 v57, 16, v53
	v_and_b32_e32 v53, 0xffff0000, v53
	v_fmac_f32_e32 v51, v56, v56
	v_add_f32_e32 v50, v51, v50
	v_mul_f32_e32 v51, v53, v53
	v_fmac_f32_e32 v51, v57, v57
	v_add_f32_e32 v50, v51, v50
	ds_bpermute_b32 v147, v229, v146
	ds_bpermute_b32 v51, v229, v50
	s_waitcnt lgkmcnt(1)
	v_add_f32_e32 v146, v146, v147
	s_waitcnt lgkmcnt(0)
	v_add_f32_e32 v50, v50, v51
	ds_bpermute_b32 v147, v228, v146
	ds_bpermute_b32 v51, v228, v50
	s_and_saveexec_b64 s[10:11], vcc
	s_cbranch_execz .LBB0_958
	s_lshl_b32 s20, s82, 2
	v_lshl_add_u64 v[52:53], s[4:5], 0, v[142:143]
	s_ashr_i32 s21, s20, 31
	v_lshl_add_u64 v[52:53], s[20:21], 2, v[52:53]
	s_lshl_b32 s76, s19, 2
	v_lshl_add_u64 v[52:53], v[52:53], 0, s[76:77]
	s_waitcnt lgkmcnt(0)
	v_add_f32_e32 v50, v50, v51
	global_store_dword v[52:53], v50, off
.LBB0_958:
	s_or_b64 exec, exec, s[10:11]
	v_add_f32_e32 v50, v150, v151
	v_fmamk_f32 v50, v50, 0x3a800000, v240
	v_rsq_f32_e32 v54, v50
	s_waitcnt vmcnt(13)
	v_lshlrev_b32_e32 v52, 16, v106
	v_and_b32_e32 v53, 0xffff0000, v106
	v_mul_f32_e32 v46, v46, v54
	v_mul_f32_e32 v47, v47, v54
	v_mul_f32_e32 v46, 0xbfb8aa3b, v46
	v_mul_f32_e32 v47, 0xbfb8aa3b, v47
	v_mul_f32_e32 v48, v48, v54
	v_mul_f32_e32 v49, v49, v54
	v_exp_f32_e32 v50, v46
	v_exp_f32_e32 v47, v47
	v_mul_f32_e32 v48, 0xbfb8aa3b, v48
	v_mul_f32_e32 v49, 0xbfb8aa3b, v49
	v_mul_f32_e32 v42, v42, v54
	v_mul_f32_e32 v43, v43, v54
	v_exp_f32_e32 v48, v48
	v_exp_f32_e32 v49, v49
	v_mul_f32_e32 v42, 0xbfb8aa3b, v42
	v_mul_f32_e32 v43, 0xbfb8aa3b, v43
	v_exp_f32_e32 v42, v42
	v_exp_f32_e32 v43, v43
	v_mul_f32_e32 v44, v44, v54
	v_add_f32_e32 v50, 1.0, v50
	v_add_f32_e32 v47, 1.0, v47
	v_mul_f32_e32 v44, 0xbfb8aa3b, v44
	v_rcp_f32_e32 v50, v50
	s_waitcnt lgkmcnt(0)
	v_rcp_f32_e32 v51, v47
	v_add_f32_e32 v48, 1.0, v48
	v_add_f32_e32 v49, 1.0, v49
	v_exp_f32_e32 v55, v44
	v_mul_f32_e32 v44, v45, v54
	v_rcp_f32_e32 v48, v48
	v_rcp_f32_e32 v49, v49
	v_add_f32_e32 v42, 1.0, v42
	v_add_f32_e32 v43, 1.0, v43
	v_mul_f32_e32 v44, 0xbfb8aa3b, v44
	v_rcp_f32_e32 v42, v42
	v_rcp_f32_e32 v43, v43
	v_exp_f32_e32 v56, v44
	v_lshlrev_b32_e32 v46, 16, v110
	v_and_b32_e32 v47, 0xffff0000, v110
	v_pk_fma_f32 v[46:47], v[50:51], v[52:53], v[46:47]
	v_lshlrev_b32_e32 v50, 16, v111
	v_and_b32_e32 v51, 0xffff0000, v111
	v_lshlrev_b32_e32 v52, 16, v107
	v_and_b32_e32 v53, 0xffff0000, v107
	v_pk_fma_f32 v[48:49], v[48:49], v[52:53], v[50:51]
	v_lshlrev_b32_e32 v50, 16, v112
	v_and_b32_e32 v51, 0xffff0000, v112
	v_lshlrev_b32_e32 v52, 16, v108
	v_and_b32_e32 v53, 0xffff0000, v108
	v_pk_fma_f32 v[44:45], v[42:43], v[52:53], v[50:51]
	v_add_f32_e32 v42, 1.0, v55
	v_add_f32_e32 v43, 1.0, v56
	v_rcp_f32_e32 v42, v42
	v_rcp_f32_e32 v43, v43
	v_lshlrev_b32_e32 v50, 16, v113
	v_and_b32_e32 v51, 0xffff0000, v113
	v_lshlrev_b32_e32 v52, 16, v109
	v_and_b32_e32 v53, 0xffff0000, v109
	v_pk_fma_f32 v[50:51], v[42:43], v[52:53], v[50:51]
	v_cvt_pk_bf16_f32 v42, v46, v47
	v_mul_f32_e32 v38, v38, v54
	v_mul_f32_e32 v39, v39, v54
	v_cvt_pk_bf16_f32 v43, v48, v49
	v_and_b32_e32 v47, 0xffff0000, v42
	v_mul_f32_e32 v38, 0xbfb8aa3b, v38
	v_mul_f32_e32 v39, 0xbfb8aa3b, v39
	v_mul_f32_e32 v40, v40, v54
	v_mul_f32_e32 v41, v41, v54
	v_lshlrev_b32_e32 v46, 16, v42
	v_and_b32_e32 v49, 0xffff0000, v43
	v_mul_f32_e32 v47, v47, v47
	v_exp_f32_e32 v38, v38
	v_exp_f32_e32 v39, v39
	v_mul_f32_e32 v40, 0xbfb8aa3b, v40
	v_mul_f32_e32 v41, 0xbfb8aa3b, v41
	v_cvt_pk_bf16_f32 v44, v44, v45
	v_lshlrev_b32_e32 v48, 16, v43
	v_fmac_f32_e32 v47, v46, v46
	v_mul_f32_e32 v46, v49, v49
	v_exp_f32_e32 v40, v40
	v_exp_f32_e32 v41, v41
	v_cvt_pk_bf16_f32 v45, v50, v51
	v_and_b32_e32 v51, 0xffff0000, v44
	v_fmac_f32_e32 v46, v48, v48
	v_mul_f32_e32 v34, v34, v54
	v_lshlrev_b32_e32 v50, 16, v44
	v_add_f32_e32 v46, v47, v46
	v_mul_f32_e32 v47, v51, v51
	v_mul_f32_e32 v34, 0xbfb8aa3b, v34
	v_and_b32_e32 v53, 0xffff0000, v45
	v_fmac_f32_e32 v47, v50, v50
	v_add_f32_e32 v38, 1.0, v38
	v_add_f32_e32 v39, 1.0, v39
	v_exp_f32_e32 v51, v34
	v_mul_f32_e32 v34, v35, v54
	v_lshlrev_b32_e32 v52, 16, v45
	v_add_f32_e32 v46, v47, v46
	v_mul_f32_e32 v47, v53, v53
	v_rcp_f32_e32 v38, v38
	v_rcp_f32_e32 v39, v39
	v_add_f32_e32 v40, 1.0, v40
	v_add_f32_e32 v41, 1.0, v41
	v_mul_f32_e32 v34, 0xbfb8aa3b, v34
	v_mul_f32_e32 v36, v36, v54
	v_mul_f32_e32 v37, v37, v54
	v_fmac_f32_e32 v47, v52, v52
	v_rcp_f32_e32 v40, v40
	v_rcp_f32_e32 v41, v41
	v_exp_f32_e32 v52, v34
	v_mul_f32_e32 v36, 0xbfb8aa3b, v36
	v_mul_f32_e32 v37, 0xbfb8aa3b, v37
	v_exp_f32_e32 v36, v36
	v_exp_f32_e32 v37, v37
	v_add_f32_e32 v50, v47, v46
	s_waitcnt vmcnt(12)
	v_lshlrev_b32_e32 v46, 16, v102
	v_and_b32_e32 v47, 0xffff0000, v102
	s_waitcnt vmcnt(11)
	v_lshlrev_b32_e32 v48, 16, v98
	v_and_b32_e32 v49, 0xffff0000, v98
	v_pk_fma_f32 v[38:39], v[38:39], v[48:49], v[46:47]
	v_lshlrev_b32_e32 v46, 16, v103
	v_and_b32_e32 v47, 0xffff0000, v103
	v_lshlrev_b32_e32 v48, 16, v99
	v_and_b32_e32 v49, 0xffff0000, v99
	v_pk_fma_f32 v[34:35], v[40:41], v[48:49], v[46:47]
	v_add_f32_e32 v40, 1.0, v51
	v_add_f32_e32 v41, 1.0, v52
	v_rcp_f32_e32 v40, v40
	v_rcp_f32_e32 v41, v41
	v_add_f32_e32 v36, 1.0, v36
	v_add_f32_e32 v37, 1.0, v37
	v_rcp_f32_e32 v36, v36
	v_rcp_f32_e32 v37, v37
	v_lshlrev_b32_e32 v46, 16, v104
	v_and_b32_e32 v47, 0xffff0000, v104
	v_lshlrev_b32_e32 v48, 16, v100
	v_and_b32_e32 v49, 0xffff0000, v100
	v_pk_fma_f32 v[40:41], v[40:41], v[48:49], v[46:47]
	v_lshlrev_b32_e32 v46, 16, v105
	v_and_b32_e32 v47, 0xffff0000, v105
	v_lshlrev_b32_e32 v48, 16, v101
	v_and_b32_e32 v49, 0xffff0000, v101
	v_pk_fma_f32 v[46:47], v[36:37], v[48:49], v[46:47]
	v_cvt_pk_bf16_f32 v36, v38, v39
	v_cvt_pk_bf16_f32 v37, v34, v35
	v_and_b32_e32 v35, 0xffff0000, v36
	v_lshlrev_b32_e32 v34, 16, v36
	v_mul_f32_e32 v35, v35, v35
	v_cvt_pk_bf16_f32 v38, v40, v41
	v_and_b32_e32 v41, 0xffff0000, v37
	v_fmac_f32_e32 v35, v34, v34
	v_lshlrev_b32_e32 v40, 16, v37
	v_add_f32_e32 v34, v35, v50
	v_mul_f32_e32 v35, v41, v41
	v_cvt_pk_bf16_f32 v39, v46, v47
	v_and_b32_e32 v47, 0xffff0000, v38
	v_fmac_f32_e32 v35, v40, v40
	v_lshlrev_b32_e32 v46, 16, v38
	v_add_f32_e32 v34, v35, v34
	v_mul_f32_e32 v35, v47, v47
	v_and_b32_e32 v49, 0xffff0000, v39
	v_fmac_f32_e32 v35, v46, v46
	v_lshlrev_b32_e32 v48, 16, v39
	v_add_f32_e32 v34, v35, v34
	v_mul_f32_e32 v35, v49, v49
	v_fmac_f32_e32 v35, v48, v48
	v_add_f32_e32 v34, v35, v34
	ds_bpermute_b32 v35, v229, v34
	v_lshlrev_b64 v[40:41], 11, v[140:141]
	v_lshl_add_u64 v[40:41], s[92:93], 0, v[40:41]
	v_lshl_add_u64 v[40:41], v[204:205], 1, v[40:41]
	global_store_dwordx4 v[40:41], v[42:45], off
	global_store_dwordx4 v[40:41], v[36:39], off offset:256
	s_waitcnt lgkmcnt(0)
	v_add_f32_e32 v34, v34, v35
	ds_bpermute_b32 v35, v228, v34
	s_and_saveexec_b64 s[10:11], vcc
	s_cbranch_execz .LBB0_960
	s_lshl_b32 s20, s82, 2
	v_lshl_add_u64 v[36:37], s[4:5], 0, v[138:139]
	s_ashr_i32 s21, s20, 31
	v_lshl_add_u64 v[36:37], s[20:21], 2, v[36:37]
	s_lshl_b32 s76, s19, 2
	v_lshl_add_u64 v[36:37], v[36:37], 0, s[76:77]
	s_waitcnt lgkmcnt(0)
	v_add_f32_e32 v34, v34, v35
	global_store_dword v[36:37], v34, off
.LBB0_960:
	s_or_b64 exec, exec, s[10:11]
	v_add_f32_e32 v34, v148, v149
	v_fmamk_f32 v34, v34, 0x3a800000, v240
	v_rsq_f32_e32 v38, v34
	s_waitcnt vmcnt(12)
	v_lshlrev_b32_e32 v36, 16, v90
	v_and_b32_e32 v37, 0xffff0000, v90
	v_mul_f32_e32 v30, v30, v38
	v_mul_f32_e32 v31, v31, v38
	v_mul_f32_e32 v30, 0xbfb8aa3b, v30
	v_mul_f32_e32 v31, 0xbfb8aa3b, v31
	v_mul_f32_e32 v32, v32, v38
	v_mul_f32_e32 v33, v33, v38
	v_exp_f32_e32 v34, v30
	v_exp_f32_e32 v31, v31
	v_mul_f32_e32 v32, 0xbfb8aa3b, v32
	v_mul_f32_e32 v33, 0xbfb8aa3b, v33
	v_mul_f32_e32 v26, v26, v38
	v_mul_f32_e32 v27, v27, v38
	v_exp_f32_e32 v32, v32
	v_exp_f32_e32 v33, v33
	v_mul_f32_e32 v26, 0xbfb8aa3b, v26
	v_mul_f32_e32 v27, 0xbfb8aa3b, v27
	v_exp_f32_e32 v26, v26
	v_exp_f32_e32 v27, v27
	v_mul_f32_e32 v28, v28, v38
	v_add_f32_e32 v34, 1.0, v34
	v_add_f32_e32 v31, 1.0, v31
	v_mul_f32_e32 v28, 0xbfb8aa3b, v28
	v_rcp_f32_e32 v34, v34
	s_waitcnt lgkmcnt(0)
	v_rcp_f32_e32 v35, v31
	v_add_f32_e32 v32, 1.0, v32
	v_add_f32_e32 v33, 1.0, v33
	v_exp_f32_e32 v39, v28
	v_mul_f32_e32 v28, v29, v38
	v_rcp_f32_e32 v32, v32
	v_rcp_f32_e32 v33, v33
	v_add_f32_e32 v26, 1.0, v26
	v_add_f32_e32 v27, 1.0, v27
	v_mul_f32_e32 v28, 0xbfb8aa3b, v28
	v_rcp_f32_e32 v26, v26
	v_rcp_f32_e32 v27, v27
	v_exp_f32_e32 v40, v28
	v_lshlrev_b32_e32 v30, 16, v94
	v_and_b32_e32 v31, 0xffff0000, v94
	v_pk_fma_f32 v[30:31], v[34:35], v[36:37], v[30:31]
	v_lshlrev_b32_e32 v34, 16, v95
	v_and_b32_e32 v35, 0xffff0000, v95
	v_lshlrev_b32_e32 v36, 16, v91
	v_and_b32_e32 v37, 0xffff0000, v91
	v_pk_fma_f32 v[32:33], v[32:33], v[36:37], v[34:35]
	v_lshlrev_b32_e32 v34, 16, v96
	v_and_b32_e32 v35, 0xffff0000, v96
	v_lshlrev_b32_e32 v36, 16, v92
	v_and_b32_e32 v37, 0xffff0000, v92
	v_pk_fma_f32 v[28:29], v[26:27], v[36:37], v[34:35]
	v_add_f32_e32 v26, 1.0, v39
	v_add_f32_e32 v27, 1.0, v40
	v_rcp_f32_e32 v26, v26
	v_rcp_f32_e32 v27, v27
	v_lshlrev_b32_e32 v34, 16, v97
	v_and_b32_e32 v35, 0xffff0000, v97
	v_lshlrev_b32_e32 v36, 16, v93
	v_and_b32_e32 v37, 0xffff0000, v93
	v_pk_fma_f32 v[34:35], v[26:27], v[36:37], v[34:35]
	v_cvt_pk_bf16_f32 v26, v30, v31
	v_mul_f32_e32 v22, v22, v38
	v_mul_f32_e32 v23, v23, v38
	v_cvt_pk_bf16_f32 v27, v32, v33
	v_and_b32_e32 v31, 0xffff0000, v26
	v_mul_f32_e32 v22, 0xbfb8aa3b, v22
	v_mul_f32_e32 v23, 0xbfb8aa3b, v23
	v_mul_f32_e32 v24, v24, v38
	v_mul_f32_e32 v25, v25, v38
	v_lshlrev_b32_e32 v30, 16, v26
	v_and_b32_e32 v33, 0xffff0000, v27
	v_mul_f32_e32 v31, v31, v31
	v_exp_f32_e32 v22, v22
	v_exp_f32_e32 v23, v23
	v_mul_f32_e32 v24, 0xbfb8aa3b, v24
	v_mul_f32_e32 v25, 0xbfb8aa3b, v25
	v_cvt_pk_bf16_f32 v28, v28, v29
	v_lshlrev_b32_e32 v32, 16, v27
	v_fmac_f32_e32 v31, v30, v30
	v_mul_f32_e32 v30, v33, v33
	v_exp_f32_e32 v24, v24
	v_exp_f32_e32 v25, v25
	v_cvt_pk_bf16_f32 v29, v34, v35
	v_and_b32_e32 v35, 0xffff0000, v28
	v_fmac_f32_e32 v30, v32, v32
	v_mul_f32_e32 v18, v18, v38
	v_lshlrev_b32_e32 v34, 16, v28
	v_add_f32_e32 v30, v31, v30
	v_mul_f32_e32 v31, v35, v35
	v_mul_f32_e32 v18, 0xbfb8aa3b, v18
	v_and_b32_e32 v37, 0xffff0000, v29
	v_fmac_f32_e32 v31, v34, v34
	v_add_f32_e32 v22, 1.0, v22
	v_add_f32_e32 v23, 1.0, v23
	v_exp_f32_e32 v35, v18
	v_mul_f32_e32 v18, v19, v38
	v_lshlrev_b32_e32 v36, 16, v29
	v_add_f32_e32 v30, v31, v30
	v_mul_f32_e32 v31, v37, v37
	v_rcp_f32_e32 v22, v22
	v_rcp_f32_e32 v23, v23
	v_add_f32_e32 v24, 1.0, v24
	v_add_f32_e32 v25, 1.0, v25
	v_mul_f32_e32 v18, 0xbfb8aa3b, v18
	v_mul_f32_e32 v20, v20, v38
	v_mul_f32_e32 v21, v21, v38
	v_fmac_f32_e32 v31, v36, v36
	v_rcp_f32_e32 v24, v24
	v_rcp_f32_e32 v25, v25
	v_exp_f32_e32 v36, v18
	v_mul_f32_e32 v20, 0xbfb8aa3b, v20
	v_mul_f32_e32 v21, 0xbfb8aa3b, v21
	v_exp_f32_e32 v20, v20
	v_exp_f32_e32 v21, v21
	v_add_f32_e32 v34, v31, v30
	s_waitcnt vmcnt(11)
	v_lshlrev_b32_e32 v30, 16, v86
	v_and_b32_e32 v31, 0xffff0000, v86
	s_waitcnt vmcnt(10)
	v_lshlrev_b32_e32 v32, 16, v82
	v_and_b32_e32 v33, 0xffff0000, v82
	v_pk_fma_f32 v[22:23], v[22:23], v[32:33], v[30:31]
	v_lshlrev_b32_e32 v30, 16, v87
	v_and_b32_e32 v31, 0xffff0000, v87
	v_lshlrev_b32_e32 v32, 16, v83
	v_and_b32_e32 v33, 0xffff0000, v83
	v_pk_fma_f32 v[18:19], v[24:25], v[32:33], v[30:31]
	v_add_f32_e32 v24, 1.0, v35
	v_add_f32_e32 v25, 1.0, v36
	v_rcp_f32_e32 v24, v24
	v_rcp_f32_e32 v25, v25
	v_add_f32_e32 v20, 1.0, v20
	v_add_f32_e32 v21, 1.0, v21
	v_rcp_f32_e32 v20, v20
	v_rcp_f32_e32 v21, v21
	v_lshlrev_b32_e32 v30, 16, v88
	v_and_b32_e32 v31, 0xffff0000, v88
	v_lshlrev_b32_e32 v32, 16, v84
	v_and_b32_e32 v33, 0xffff0000, v84
	v_pk_fma_f32 v[24:25], v[24:25], v[32:33], v[30:31]
	v_lshlrev_b32_e32 v30, 16, v89
	v_and_b32_e32 v31, 0xffff0000, v89
	v_lshlrev_b32_e32 v32, 16, v85
	v_and_b32_e32 v33, 0xffff0000, v85
	v_pk_fma_f32 v[30:31], v[20:21], v[32:33], v[30:31]
	v_cvt_pk_bf16_f32 v20, v22, v23
	v_cvt_pk_bf16_f32 v21, v18, v19
	v_and_b32_e32 v19, 0xffff0000, v20
	v_lshlrev_b32_e32 v18, 16, v20
	v_mul_f32_e32 v19, v19, v19
	v_cvt_pk_bf16_f32 v22, v24, v25
	v_and_b32_e32 v25, 0xffff0000, v21
	v_fmac_f32_e32 v19, v18, v18
	v_lshlrev_b32_e32 v24, 16, v21
	v_add_f32_e32 v18, v19, v34
	v_mul_f32_e32 v19, v25, v25
	v_cvt_pk_bf16_f32 v23, v30, v31
	v_and_b32_e32 v31, 0xffff0000, v22
	v_fmac_f32_e32 v19, v24, v24
	v_lshlrev_b32_e32 v30, 16, v22
	v_add_f32_e32 v18, v19, v18
	v_mul_f32_e32 v19, v31, v31
	v_and_b32_e32 v33, 0xffff0000, v23
	v_fmac_f32_e32 v19, v30, v30
	v_lshlrev_b32_e32 v32, 16, v23
	v_add_f32_e32 v18, v19, v18
	v_mul_f32_e32 v19, v33, v33
	v_fmac_f32_e32 v19, v32, v32
	v_add_f32_e32 v18, v19, v18
	ds_bpermute_b32 v19, v229, v18
	v_lshlrev_b64 v[24:25], 11, v[134:135]
	v_lshl_add_u64 v[24:25], s[92:93], 0, v[24:25]
	v_lshl_add_u64 v[24:25], v[204:205], 1, v[24:25]
	global_store_dwordx4 v[24:25], v[26:29], off
	global_store_dwordx4 v[24:25], v[20:23], off offset:256
	s_waitcnt lgkmcnt(0)
	v_add_f32_e32 v18, v18, v19
	ds_bpermute_b32 v19, v228, v18
	s_and_saveexec_b64 s[10:11], vcc
	s_cbranch_execz .LBB0_962
	s_lshl_b32 s20, s82, 2
	v_lshl_add_u64 v[20:21], s[4:5], 0, v[136:137]
	s_ashr_i32 s21, s20, 31
	v_lshl_add_u64 v[20:21], s[20:21], 2, v[20:21]
	s_lshl_b32 s76, s19, 2
	v_lshl_add_u64 v[20:21], v[20:21], 0, s[76:77]
	s_waitcnt lgkmcnt(0)
	v_add_f32_e32 v18, v18, v19
	global_store_dword v[20:21], v18, off
.LBB0_962:
	s_or_b64 exec, exec, s[10:11]
	v_add_f32_e32 v18, v146, v147
	v_fmamk_f32 v18, v18, 0x3a800000, v240
	v_rsq_f32_e32 v22, v18
	s_waitcnt vmcnt(11)
	v_lshlrev_b32_e32 v20, 16, v74
	v_and_b32_e32 v21, 0xffff0000, v74
	v_mul_f32_e32 v14, v14, v22
	v_mul_f32_e32 v15, v15, v22
	v_mul_f32_e32 v14, 0xbfb8aa3b, v14
	v_mul_f32_e32 v15, 0xbfb8aa3b, v15
	v_mul_f32_e32 v16, v16, v22
	v_mul_f32_e32 v17, v17, v22
	v_exp_f32_e32 v18, v14
	v_exp_f32_e32 v15, v15
	v_mul_f32_e32 v16, 0xbfb8aa3b, v16
	v_mul_f32_e32 v17, 0xbfb8aa3b, v17
	v_mul_f32_e32 v10, v10, v22
	v_mul_f32_e32 v11, v11, v22
	v_exp_f32_e32 v16, v16
	v_exp_f32_e32 v17, v17
	v_mul_f32_e32 v10, 0xbfb8aa3b, v10
	v_mul_f32_e32 v11, 0xbfb8aa3b, v11
	v_exp_f32_e32 v10, v10
	v_exp_f32_e32 v11, v11
	v_mul_f32_e32 v12, v12, v22
	v_add_f32_e32 v18, 1.0, v18
	v_add_f32_e32 v15, 1.0, v15
	v_mul_f32_e32 v12, 0xbfb8aa3b, v12
	v_rcp_f32_e32 v18, v18
	s_waitcnt lgkmcnt(0)
	v_rcp_f32_e32 v19, v15
	v_add_f32_e32 v16, 1.0, v16
	v_add_f32_e32 v17, 1.0, v17
	v_exp_f32_e32 v23, v12
	v_mul_f32_e32 v12, v13, v22
	v_rcp_f32_e32 v16, v16
	v_rcp_f32_e32 v17, v17
	v_add_f32_e32 v10, 1.0, v10
	v_add_f32_e32 v11, 1.0, v11
	v_mul_f32_e32 v12, 0xbfb8aa3b, v12
	v_rcp_f32_e32 v10, v10
	v_rcp_f32_e32 v11, v11
	v_exp_f32_e32 v24, v12
	v_lshlrev_b32_e32 v14, 16, v78
	v_and_b32_e32 v15, 0xffff0000, v78
	v_pk_fma_f32 v[14:15], v[18:19], v[20:21], v[14:15]
	v_lshlrev_b32_e32 v18, 16, v79
	v_and_b32_e32 v19, 0xffff0000, v79
	v_lshlrev_b32_e32 v20, 16, v75
	v_and_b32_e32 v21, 0xffff0000, v75
	v_pk_fma_f32 v[16:17], v[16:17], v[20:21], v[18:19]
	v_lshlrev_b32_e32 v18, 16, v80
	v_and_b32_e32 v19, 0xffff0000, v80
	v_lshlrev_b32_e32 v20, 16, v76
	v_and_b32_e32 v21, 0xffff0000, v76
	v_pk_fma_f32 v[12:13], v[10:11], v[20:21], v[18:19]
	v_add_f32_e32 v10, 1.0, v23
	v_add_f32_e32 v11, 1.0, v24
	v_rcp_f32_e32 v10, v10
	v_rcp_f32_e32 v11, v11
	v_lshlrev_b32_e32 v18, 16, v81
	v_and_b32_e32 v19, 0xffff0000, v81
	v_lshlrev_b32_e32 v20, 16, v77
	v_and_b32_e32 v21, 0xffff0000, v77
	v_pk_fma_f32 v[18:19], v[10:11], v[20:21], v[18:19]
	v_cvt_pk_bf16_f32 v10, v14, v15
	v_mul_f32_e32 v6, v6, v22
	v_mul_f32_e32 v7, v7, v22
	v_cvt_pk_bf16_f32 v11, v16, v17
	v_and_b32_e32 v15, 0xffff0000, v10
	v_mul_f32_e32 v6, 0xbfb8aa3b, v6
	v_mul_f32_e32 v7, 0xbfb8aa3b, v7
	v_mul_f32_e32 v8, v8, v22
	v_mul_f32_e32 v9, v9, v22
	v_lshlrev_b32_e32 v14, 16, v10
	v_and_b32_e32 v17, 0xffff0000, v11
	v_mul_f32_e32 v15, v15, v15
	v_exp_f32_e32 v6, v6
	v_exp_f32_e32 v7, v7
	v_mul_f32_e32 v8, 0xbfb8aa3b, v8
	v_mul_f32_e32 v9, 0xbfb8aa3b, v9
	v_cvt_pk_bf16_f32 v12, v12, v13
	v_lshlrev_b32_e32 v16, 16, v11
	v_fmac_f32_e32 v15, v14, v14
	v_mul_f32_e32 v14, v17, v17
	v_exp_f32_e32 v8, v8
	v_exp_f32_e32 v9, v9
	v_cvt_pk_bf16_f32 v13, v18, v19
	v_and_b32_e32 v19, 0xffff0000, v12
	v_fmac_f32_e32 v14, v16, v16
	v_mul_f32_e32 v2, v2, v22
	v_lshlrev_b32_e32 v18, 16, v12
	v_add_f32_e32 v14, v15, v14
	v_mul_f32_e32 v15, v19, v19
	v_mul_f32_e32 v2, 0xbfb8aa3b, v2
	v_and_b32_e32 v21, 0xffff0000, v13
	v_fmac_f32_e32 v15, v18, v18
	v_add_f32_e32 v6, 1.0, v6
	v_add_f32_e32 v7, 1.0, v7
	v_exp_f32_e32 v19, v2
	v_mul_f32_e32 v2, v3, v22
	v_lshlrev_b32_e32 v20, 16, v13
	v_add_f32_e32 v14, v15, v14
	v_mul_f32_e32 v15, v21, v21
	v_rcp_f32_e32 v6, v6
	v_rcp_f32_e32 v7, v7
	v_add_f32_e32 v8, 1.0, v8
	v_add_f32_e32 v9, 1.0, v9
	v_mul_f32_e32 v2, 0xbfb8aa3b, v2
	v_mul_f32_e32 v4, v4, v22
	v_mul_f32_e32 v5, v5, v22
	v_fmac_f32_e32 v15, v20, v20
	v_rcp_f32_e32 v8, v8
	v_rcp_f32_e32 v9, v9
	v_exp_f32_e32 v20, v2
	v_mul_f32_e32 v4, 0xbfb8aa3b, v4
	v_mul_f32_e32 v5, 0xbfb8aa3b, v5
	v_exp_f32_e32 v4, v4
	v_exp_f32_e32 v5, v5
	v_add_f32_e32 v18, v15, v14
	s_waitcnt vmcnt(10)
	v_lshlrev_b32_e32 v14, 16, v70
	v_and_b32_e32 v15, 0xffff0000, v70
	s_waitcnt vmcnt(9)
	v_lshlrev_b32_e32 v16, 16, v66
	v_and_b32_e32 v17, 0xffff0000, v66
	v_pk_fma_f32 v[6:7], v[6:7], v[16:17], v[14:15]
	v_lshlrev_b32_e32 v14, 16, v71
	v_and_b32_e32 v15, 0xffff0000, v71
	v_lshlrev_b32_e32 v16, 16, v67
	v_and_b32_e32 v17, 0xffff0000, v67
	v_pk_fma_f32 v[2:3], v[8:9], v[16:17], v[14:15]
	v_add_f32_e32 v8, 1.0, v19
	v_add_f32_e32 v9, 1.0, v20
	v_rcp_f32_e32 v8, v8
	v_rcp_f32_e32 v9, v9
	v_add_f32_e32 v4, 1.0, v4
	v_add_f32_e32 v5, 1.0, v5
	v_rcp_f32_e32 v4, v4
	v_rcp_f32_e32 v5, v5
	v_lshlrev_b32_e32 v14, 16, v72
	v_and_b32_e32 v15, 0xffff0000, v72
	v_lshlrev_b32_e32 v16, 16, v68
	v_and_b32_e32 v17, 0xffff0000, v68
	v_pk_fma_f32 v[8:9], v[8:9], v[16:17], v[14:15]
	v_lshlrev_b32_e32 v14, 16, v73
	v_and_b32_e32 v15, 0xffff0000, v73
	v_lshlrev_b32_e32 v16, 16, v69
	v_and_b32_e32 v17, 0xffff0000, v69
	v_pk_fma_f32 v[14:15], v[4:5], v[16:17], v[14:15]
	v_cvt_pk_bf16_f32 v4, v6, v7
	v_cvt_pk_bf16_f32 v5, v2, v3
	v_and_b32_e32 v3, 0xffff0000, v4
	v_lshlrev_b32_e32 v2, 16, v4
	v_mul_f32_e32 v3, v3, v3
	v_cvt_pk_bf16_f32 v6, v8, v9
	v_and_b32_e32 v9, 0xffff0000, v5
	v_fmac_f32_e32 v3, v2, v2
	v_lshlrev_b32_e32 v8, 16, v5
	v_add_f32_e32 v2, v3, v18
	v_mul_f32_e32 v3, v9, v9
	v_cvt_pk_bf16_f32 v7, v14, v15
	v_and_b32_e32 v15, 0xffff0000, v6
	v_fmac_f32_e32 v3, v8, v8
	v_lshlrev_b32_e32 v14, 16, v6
	v_add_f32_e32 v2, v3, v2
	v_mul_f32_e32 v3, v15, v15
	v_and_b32_e32 v17, 0xffff0000, v7
	v_fmac_f32_e32 v3, v14, v14
	v_lshlrev_b32_e32 v16, 16, v7
	v_add_f32_e32 v2, v3, v2
	v_mul_f32_e32 v3, v17, v17
	v_fmac_f32_e32 v3, v16, v16
	v_add_f32_e32 v2, v3, v2
	ds_bpermute_b32 v3, v229, v2
	v_lshlrev_b64 v[8:9], 11, v[130:131]
	v_lshl_add_u64 v[8:9], s[92:93], 0, v[8:9]
	v_lshl_add_u64 v[8:9], v[204:205], 1, v[8:9]
	global_store_dwordx4 v[8:9], v[10:13], off
	global_store_dwordx4 v[8:9], v[4:7], off offset:256
	s_waitcnt lgkmcnt(0)
	v_add_f32_e32 v2, v2, v3
	ds_bpermute_b32 v3, v228, v2
	s_and_saveexec_b64 s[10:11], vcc
	s_cbranch_execz .LBB0_964
	s_lshl_b32 s20, s82, 2
	v_lshl_add_u64 v[4:5], s[4:5], 0, v[132:133]
	s_ashr_i32 s21, s20, 31
	v_lshl_add_u64 v[4:5], s[20:21], 2, v[4:5]
	s_lshl_b32 s76, s19, 2
	v_lshl_add_u64 v[4:5], v[4:5], 0, s[76:77]
	s_waitcnt lgkmcnt(0)
	v_add_f32_e32 v2, v2, v3
	global_store_dword v[4:5], v2, off
